# epilogue dead address arithmetic removed (block-local DCE); SwiGLU stores use SGPR tile base + 32-bit lane offset instead of 64-bit multiply-add chains
# baseline (speedup 1.0000x reference)
.LBB0_380:
	s_lshl_b32 s5, s5, 8
	s_lshl_b32 s6, s6, 7
	s_add_i32 s5, s5, s6
	v_add_u32_e32 v130, s5, v222
	v_ashrrev_i32_e32 v131, 31, v130
	v_lshlrev_b64 v[132:133], 6, v[130:131]
	v_lshl_add_u64 v[132:133], v[204:205], 0, v[132:133]
	global_load_dwordx4 v[136:139], v[132:133], off
	global_load_dwordx4 v[140:143], v[132:133], off offset:1024
	global_load_dwordx4 v[144:147], v[132:133], off offset:2048
	global_load_dwordx4 v[148:151], v[132:133], off offset:3072
	v_add_u32_e32 v168, 0x80, v130
	v_ashrrev_i32_e32 v169, 31, v168
	v_lshlrev_b64 v[168:169], 6, v[168:169]
	v_lshl_add_u64 v[168:169], v[204:205], 0, v[168:169]
	global_load_dwordx4 v[152:155], v[168:169], off
	global_load_dwordx4 v[156:159], v[168:169], off offset:1024
	global_load_dwordx4 v[160:163], v[168:169], off offset:2048
	global_load_dwordx4 v[164:167], v[168:169], off offset:3072
	s_lshl_b32 s4, s4, 7
	s_ashr_i32 s5, s4, 31
	s_lshl_b64 s[38:39], s[4:5], 1
	s_add_u32 s6, s62, s38
	s_addc_u32 s7, s63, s39
	s_add_u32 s6, s6, s68
	s_addc_u32 s7, s7, s69
	s_waitcnt vmcnt(7)
	v_add_f32_e32 v131, v136, v137
	v_add_f32_e32 v132, v138, v139
	v_add_f32_e32 v131, v131, v132
	v_mov_b32_e32 v132, v131
	s_nop 1
	v_permlane16_swap_b32_e32 v131, v132
	v_add_f32_e32 v131, v131, v132
	v_mov_b32_e32 v132, v131
	s_nop 1
	v_permlane32_swap_b32_e32 v131, v132
	v_add_f32_e32 v131, v131, v132
	v_fmamk_f32 v131, v131, 0x3a800000, v225
	v_rsq_f32_e32 v132, v131
	s_nop 0
	v_mul_f32_e32 v133, v132, v132
	v_mul_f32_e32 v132, 0xbfb8aa3b, v132
	v_pk_mul_f32 v[134:135], v[126:127], v[132:133] op_sel_hi:[1,0]
	v_pk_mul_f32 v[126:127], v[126:127], v[122:123]
	v_pk_mul_f32 v[122:123], v[128:129], v[132:133] op_sel_hi:[1,0]
	v_pk_mul_f32 v[128:129], v[128:129], v[124:125]
	v_exp_f32_e32 v134, v134
	v_exp_f32_e32 v135, v135
	v_exp_f32_e32 v122, v122
	v_exp_f32_e32 v123, v123
	v_pk_add_f32 v[134:135], v[134:135], 1.0 op_sel_hi:[1,0]
	v_pk_add_f32 v[122:123], v[122:123], 1.0 op_sel_hi:[1,0]
	v_rcp_f32_e32 v134, v134
	v_rcp_f32_e32 v135, v135
	v_rcp_f32_e32 v122, v122
	v_rcp_f32_e32 v123, v123
	v_pk_mul_f32 v[134:135], v[134:135], v[132:133] op_sel:[0,1]
	v_pk_mul_f32 v[122:123], v[122:123], v[132:133] op_sel:[0,1]
	s_nop 0
	v_pk_mul_f32 v[124:125], v[128:129], v[122:123]
	v_pk_mul_f32 v[122:123], v[126:127], v[134:135]
	v_pk_mul_f32 v[134:135], v[118:119], v[132:133] op_sel_hi:[1,0]
	v_pk_mul_f32 v[118:119], v[118:119], v[114:115]
	v_pk_mul_f32 v[126:127], v[120:121], v[132:133] op_sel_hi:[1,0]
	v_pk_mul_f32 v[120:121], v[120:121], v[116:117]
	v_exp_f32_e32 v134, v134
	v_exp_f32_e32 v135, v135
	v_exp_f32_e32 v126, v126
	v_exp_f32_e32 v127, v127
	v_pk_add_f32 v[134:135], v[134:135], 1.0 op_sel_hi:[1,0]
	v_pk_add_f32 v[126:127], v[126:127], 1.0 op_sel_hi:[1,0]
	v_rcp_f32_e32 v134, v134
	v_rcp_f32_e32 v135, v135
	v_rcp_f32_e32 v126, v126
	v_rcp_f32_e32 v127, v127
	v_pk_mul_f32 v[134:135], v[134:135], v[132:133] op_sel:[0,1]
	v_pk_mul_f32 v[126:127], v[126:127], v[132:133] op_sel:[0,1]
	v_pk_mul_f32 v[118:119], v[118:119], v[134:135]
	v_pk_mul_f32 v[120:121], v[120:121], v[126:127]
	v_cvt_pk_bf16_f32 v116, v118, v119
	v_cvt_pk_bf16_f32 v117, v120, v121
	v_cvt_pk_bf16_f32 v114, v122, v123
	v_cvt_pk_bf16_f32 v115, v124, v125
	v_mad_u32_u24 v120, v130, s16, v96
	global_store_dwordx4 v120, v[114:117], s[6:7] sc1
	s_nop 1
	v_or_b32_e32 v114, 16, v130
	s_waitcnt vmcnt(7)
	v_add_f32_e32 v115, v140, v141
	v_add_f32_e32 v116, v142, v143
	v_add_f32_e32 v115, v115, v116
	v_mov_b32_e32 v116, v115
	s_nop 1
	v_permlane16_swap_b32_e32 v115, v116
	v_add_f32_e32 v115, v115, v116
	v_mov_b32_e32 v116, v115
	s_nop 1
	v_permlane32_swap_b32_e32 v115, v116
	v_add_f32_e32 v115, v115, v116
	v_fmamk_f32 v115, v115, 0x3a800000, v225
	v_rsq_f32_e32 v116, v115
	s_nop 0
	v_mul_f32_e32 v117, v116, v116
	v_mul_f32_e32 v116, 0xbfb8aa3b, v116
	v_pk_mul_f32 v[120:121], v[110:111], v[116:117] op_sel_hi:[1,0]
	v_pk_mul_f32 v[110:111], v[110:111], v[106:107]
	v_pk_mul_f32 v[106:107], v[112:113], v[116:117] op_sel_hi:[1,0]
	v_pk_mul_f32 v[112:113], v[112:113], v[108:109]
	v_exp_f32_e32 v120, v120
	v_exp_f32_e32 v121, v121
	v_exp_f32_e32 v106, v106
	v_exp_f32_e32 v107, v107
	v_pk_add_f32 v[120:121], v[120:121], 1.0 op_sel_hi:[1,0]
	v_pk_add_f32 v[106:107], v[106:107], 1.0 op_sel_hi:[1,0]
	v_rcp_f32_e32 v120, v120
	v_rcp_f32_e32 v121, v121
	v_rcp_f32_e32 v106, v106
	v_rcp_f32_e32 v107, v107
	v_pk_mul_f32 v[120:121], v[120:121], v[116:117] op_sel:[0,1]
	v_pk_mul_f32 v[106:107], v[106:107], v[116:117] op_sel:[0,1]
	s_nop 0
	v_pk_mul_f32 v[108:109], v[112:113], v[106:107]
	v_pk_mul_f32 v[106:107], v[110:111], v[120:121]
	v_pk_mul_f32 v[120:121], v[102:103], v[116:117] op_sel_hi:[1,0]
	v_pk_mul_f32 v[102:103], v[102:103], v[98:99]
	v_pk_mul_f32 v[110:111], v[104:105], v[116:117] op_sel_hi:[1,0]
	v_pk_mul_f32 v[104:105], v[104:105], v[100:101]
	v_exp_f32_e32 v120, v120
	v_exp_f32_e32 v121, v121
	v_exp_f32_e32 v110, v110
	v_exp_f32_e32 v111, v111
	v_pk_add_f32 v[120:121], v[120:121], 1.0 op_sel_hi:[1,0]
	v_pk_add_f32 v[110:111], v[110:111], 1.0 op_sel_hi:[1,0]
	v_rcp_f32_e32 v120, v120
	v_rcp_f32_e32 v121, v121
	v_rcp_f32_e32 v110, v110
	v_rcp_f32_e32 v111, v111
	v_pk_mul_f32 v[120:121], v[120:121], v[116:117] op_sel:[0,1]
	v_pk_mul_f32 v[110:111], v[110:111], v[116:117] op_sel:[0,1]
	v_pk_mul_f32 v[102:103], v[102:103], v[120:121]
	v_pk_mul_f32 v[104:105], v[104:105], v[110:111]
	v_cvt_pk_bf16_f32 v100, v102, v103
	v_cvt_pk_bf16_f32 v98, v106, v107
	v_cvt_pk_bf16_f32 v99, v108, v109
	v_cvt_pk_bf16_f32 v101, v104, v105
	v_mad_u32_u24 v102, v114, s16, v96
	global_store_dwordx4 v102, v[98:101], s[6:7] sc1
	s_nop 1
	v_or_b32_e32 v98, 32, v130
	s_waitcnt vmcnt(7)
	v_add_f32_e32 v99, v144, v145
	v_add_f32_e32 v100, v146, v147
	v_add_f32_e32 v99, v99, v100
	v_mov_b32_e32 v100, v99
	s_nop 1
	v_permlane16_swap_b32_e32 v99, v100
	v_add_f32_e32 v99, v99, v100
	v_mov_b32_e32 v100, v99
	s_nop 1
	v_permlane32_swap_b32_e32 v99, v100
	v_add_f32_e32 v99, v99, v100
	v_fmamk_f32 v99, v99, 0x3a800000, v225
	v_rsq_f32_e32 v100, v99
	s_nop 0
	v_mul_f32_e32 v101, v100, v100
	v_mul_f32_e32 v100, 0xbfb8aa3b, v100
	v_pk_mul_f32 v[102:103], v[92:93], v[100:101] op_sel_hi:[1,0]
	v_pk_mul_f32 v[92:93], v[92:93], v[88:89]
	v_pk_mul_f32 v[88:89], v[94:95], v[100:101] op_sel_hi:[1,0]
	v_pk_mul_f32 v[94:95], v[94:95], v[90:91]
	v_exp_f32_e32 v102, v102
	v_exp_f32_e32 v103, v103
	v_exp_f32_e32 v88, v88
	v_exp_f32_e32 v89, v89
	v_pk_add_f32 v[102:103], v[102:103], 1.0 op_sel_hi:[1,0]
	v_pk_add_f32 v[88:89], v[88:89], 1.0 op_sel_hi:[1,0]
	v_rcp_f32_e32 v102, v102
	v_rcp_f32_e32 v103, v103
	v_rcp_f32_e32 v88, v88
	v_rcp_f32_e32 v89, v89
	v_pk_mul_f32 v[102:103], v[102:103], v[100:101] op_sel:[0,1]
	v_pk_mul_f32 v[88:89], v[88:89], v[100:101] op_sel:[0,1]
	s_nop 0
	v_pk_mul_f32 v[90:91], v[94:95], v[88:89]
	v_pk_mul_f32 v[88:89], v[92:93], v[102:103]
	v_pk_mul_f32 v[102:103], v[84:85], v[100:101] op_sel_hi:[1,0]
	v_pk_mul_f32 v[84:85], v[84:85], v[80:81]
	v_pk_mul_f32 v[92:93], v[86:87], v[100:101] op_sel_hi:[1,0]
	v_pk_mul_f32 v[86:87], v[86:87], v[82:83]
	v_exp_f32_e32 v102, v102
	v_exp_f32_e32 v103, v103
	v_exp_f32_e32 v92, v92
	v_exp_f32_e32 v93, v93
	v_pk_add_f32 v[102:103], v[102:103], 1.0 op_sel_hi:[1,0]
	v_pk_add_f32 v[92:93], v[92:93], 1.0 op_sel_hi:[1,0]
	v_rcp_f32_e32 v102, v102
	v_rcp_f32_e32 v103, v103
	v_rcp_f32_e32 v92, v92
	v_rcp_f32_e32 v93, v93
	v_pk_mul_f32 v[102:103], v[102:103], v[100:101] op_sel:[0,1]
	v_pk_mul_f32 v[92:93], v[92:93], v[100:101] op_sel:[0,1]
	v_pk_mul_f32 v[84:85], v[84:85], v[102:103]
	v_pk_mul_f32 v[86:87], v[86:87], v[92:93]
	v_cvt_pk_bf16_f32 v82, v84, v85
	v_cvt_pk_bf16_f32 v80, v88, v89
	v_cvt_pk_bf16_f32 v81, v90, v91
	v_cvt_pk_bf16_f32 v83, v86, v87
	v_mad_u32_u24 v84, v98, s16, v96
	global_store_dwordx4 v84, v[80:83], s[6:7] sc1
	s_nop 1
	v_or_b32_e32 v80, 48, v130
	s_waitcnt vmcnt(7)
	v_add_f32_e32 v81, v148, v149
	v_add_f32_e32 v82, v150, v151
	v_add_f32_e32 v81, v81, v82
	v_mov_b32_e32 v82, v81
	s_nop 1
	v_permlane16_swap_b32_e32 v81, v82
	v_add_f32_e32 v81, v81, v82
	v_mov_b32_e32 v82, v81
	s_nop 1
	v_permlane32_swap_b32_e32 v81, v82
	v_add_f32_e32 v81, v81, v82
	v_fmamk_f32 v81, v81, 0x3a800000, v225
	v_rsq_f32_e32 v82, v81
	s_nop 0
	v_mul_f32_e32 v83, v82, v82
	v_mul_f32_e32 v82, 0xbfb8aa3b, v82
	v_pk_mul_f32 v[84:85], v[76:77], v[82:83] op_sel_hi:[1,0]
	v_pk_mul_f32 v[76:77], v[76:77], v[72:73]
	v_pk_mul_f32 v[72:73], v[78:79], v[82:83] op_sel_hi:[1,0]
	v_pk_mul_f32 v[78:79], v[78:79], v[74:75]
	v_exp_f32_e32 v84, v84
	v_exp_f32_e32 v85, v85
	v_exp_f32_e32 v72, v72
	v_exp_f32_e32 v73, v73
	v_pk_add_f32 v[84:85], v[84:85], 1.0 op_sel_hi:[1,0]
	v_pk_add_f32 v[72:73], v[72:73], 1.0 op_sel_hi:[1,0]
	v_rcp_f32_e32 v84, v84
	v_rcp_f32_e32 v85, v85
	v_rcp_f32_e32 v72, v72
	v_rcp_f32_e32 v73, v73
	v_pk_mul_f32 v[84:85], v[84:85], v[82:83] op_sel:[0,1]
	v_pk_mul_f32 v[72:73], v[72:73], v[82:83] op_sel:[0,1]
	s_nop 0
	v_pk_mul_f32 v[74:75], v[78:79], v[72:73]
	v_pk_mul_f32 v[72:73], v[76:77], v[84:85]
	v_pk_mul_f32 v[84:85], v[68:69], v[82:83] op_sel_hi:[1,0]
	v_pk_mul_f32 v[68:69], v[68:69], v[64:65]
	v_pk_mul_f32 v[76:77], v[70:71], v[82:83] op_sel_hi:[1,0]
	v_pk_mul_f32 v[70:71], v[70:71], v[66:67]
	v_exp_f32_e32 v84, v84
	v_exp_f32_e32 v85, v85
	v_exp_f32_e32 v76, v76
	v_exp_f32_e32 v77, v77
	v_pk_add_f32 v[84:85], v[84:85], 1.0 op_sel_hi:[1,0]
	v_pk_add_f32 v[76:77], v[76:77], 1.0 op_sel_hi:[1,0]
	v_rcp_f32_e32 v84, v84
	v_rcp_f32_e32 v85, v85
	v_rcp_f32_e32 v76, v76
	v_rcp_f32_e32 v77, v77
	v_pk_mul_f32 v[84:85], v[84:85], v[82:83] op_sel:[0,1]
	v_pk_mul_f32 v[76:77], v[76:77], v[82:83] op_sel:[0,1]
	v_pk_mul_f32 v[68:69], v[68:69], v[84:85]
	v_pk_mul_f32 v[70:71], v[70:71], v[76:77]
	v_cmp_ne_u32_e32 vcc, 0, v247
	s_and_b64 vcc, exec, vcc
	v_cvt_pk_bf16_f32 v66, v68, v69
	v_cvt_pk_bf16_f32 v64, v72, v73
	v_cvt_pk_bf16_f32 v65, v74, v75
	v_cvt_pk_bf16_f32 v67, v70, v71
	v_mad_u32_u24 v68, v80, s16, v96
	global_store_dwordx4 v68, v[64:67], s[6:7] sc1
	s_cbranch_vccz .LBB0_382
	s_waitcnt vmcnt(4)
	s_and_b64 vcc, exec, s[36:37]
	s_mov_b64 s[30:31], -1
	s_cbranch_vccnz .LBB0_349
	s_branch .LBB0_383
.LBB0_382:
	s_nop 0
	v_add_u32_e32 v64, 0x80, v130
	s_waitcnt vmcnt(7)
	v_add_f32_e32 v65, v152, v153
	v_add_f32_e32 v66, v154, v155
	v_add_f32_e32 v65, v65, v66
	v_mov_b32_e32 v66, v65
	s_nop 1
	v_permlane16_swap_b32_e32 v65, v66
	v_add_f32_e32 v65, v65, v66
	v_mov_b32_e32 v66, v65
	s_nop 1
	v_permlane32_swap_b32_e32 v65, v66
	v_add_f32_e32 v65, v65, v66
	v_fmamk_f32 v65, v65, 0x3a800000, v225
	v_rsq_f32_e32 v66, v65
	s_nop 0
	v_mul_f32_e32 v67, v66, v66
	v_mul_f32_e32 v66, 0xbfb8aa3b, v66
	v_pk_mul_f32 v[68:69], v[48:49], v[66:67] op_sel_hi:[1,0]
	v_pk_mul_f32 v[48:49], v[48:49], v[60:61]
	v_pk_mul_f32 v[60:61], v[50:51], v[66:67] op_sel_hi:[1,0]
	v_pk_mul_f32 v[50:51], v[50:51], v[62:63]
	v_exp_f32_e32 v68, v68
	v_exp_f32_e32 v69, v69
	v_exp_f32_e32 v60, v60
	v_exp_f32_e32 v61, v61
	v_pk_add_f32 v[68:69], v[68:69], 1.0 op_sel_hi:[1,0]
	v_pk_add_f32 v[60:61], v[60:61], 1.0 op_sel_hi:[1,0]
	v_rcp_f32_e32 v68, v68
	v_rcp_f32_e32 v69, v69
	v_rcp_f32_e32 v60, v60
	v_rcp_f32_e32 v61, v61
	v_pk_mul_f32 v[68:69], v[68:69], v[66:67] op_sel:[0,1]
	v_pk_mul_f32 v[60:61], v[60:61], v[66:67] op_sel:[0,1]
	v_pk_mul_f32 v[48:49], v[48:49], v[68:69]
	v_pk_mul_f32 v[50:51], v[50:51], v[60:61]
	v_pk_mul_f32 v[68:69], v[56:57], v[66:67] op_sel_hi:[1,0]
	v_pk_mul_f32 v[56:57], v[56:57], v[52:53]
	v_pk_mul_f32 v[60:61], v[58:59], v[66:67] op_sel_hi:[1,0]
	v_pk_mul_f32 v[58:59], v[58:59], v[54:55]
	v_exp_f32_e32 v68, v68
	v_exp_f32_e32 v69, v69
	v_exp_f32_e32 v60, v60
	v_exp_f32_e32 v61, v61
	v_pk_add_f32 v[68:69], v[68:69], 1.0 op_sel_hi:[1,0]
	v_pk_add_f32 v[60:61], v[60:61], 1.0 op_sel_hi:[1,0]
	v_rcp_f32_e32 v68, v68
	v_rcp_f32_e32 v69, v69
	v_rcp_f32_e32 v60, v60
	v_rcp_f32_e32 v61, v61
	v_pk_mul_f32 v[68:69], v[68:69], v[66:67] op_sel:[0,1]
	v_pk_mul_f32 v[60:61], v[60:61], v[66:67] op_sel:[0,1]
	v_pk_mul_f32 v[52:53], v[56:57], v[68:69]
	v_pk_mul_f32 v[54:55], v[58:59], v[60:61]
	v_cvt_pk_bf16_f32 v48, v48, v49
	v_cvt_pk_bf16_f32 v49, v50, v51
	v_cvt_pk_bf16_f32 v50, v52, v53
	v_cvt_pk_bf16_f32 v51, v54, v55
	v_mad_u32_u24 v54, v64, s16, v96
	global_store_dwordx4 v54, v[48:51], s[6:7] sc1
	s_nop 1
	v_add_u32_e32 v48, 0x90, v130
	s_waitcnt vmcnt(7)
	v_add_f32_e32 v49, v156, v157
	v_add_f32_e32 v50, v158, v159
	v_add_f32_e32 v49, v49, v50
	v_mov_b32_e32 v50, v49
	s_nop 1
	v_permlane16_swap_b32_e32 v49, v50
	v_add_f32_e32 v49, v49, v50
	v_mov_b32_e32 v50, v49
	s_nop 1
	v_permlane32_swap_b32_e32 v49, v50
	v_add_f32_e32 v49, v49, v50
	v_fmamk_f32 v49, v49, 0x3a800000, v225
	v_rsq_f32_e32 v50, v49
	s_nop 0
	v_mul_f32_e32 v51, v50, v50
	v_mul_f32_e32 v50, 0xbfb8aa3b, v50
	v_pk_mul_f32 v[54:55], v[44:45], v[50:51] op_sel_hi:[1,0]
	v_pk_mul_f32 v[44:45], v[44:45], v[40:41]
	v_pk_mul_f32 v[40:41], v[46:47], v[50:51] op_sel_hi:[1,0]
	v_pk_mul_f32 v[46:47], v[46:47], v[42:43]
	v_exp_f32_e32 v54, v54
	v_exp_f32_e32 v55, v55
	v_exp_f32_e32 v40, v40
	v_exp_f32_e32 v41, v41
	v_pk_add_f32 v[54:55], v[54:55], 1.0 op_sel_hi:[1,0]
	v_pk_add_f32 v[40:41], v[40:41], 1.0 op_sel_hi:[1,0]
	v_rcp_f32_e32 v54, v54
	v_rcp_f32_e32 v55, v55
	v_rcp_f32_e32 v40, v40
	v_rcp_f32_e32 v41, v41
	v_pk_mul_f32 v[54:55], v[54:55], v[50:51] op_sel:[0,1]
	v_pk_mul_f32 v[40:41], v[40:41], v[50:51] op_sel:[0,1]
	s_nop 0
	v_pk_mul_f32 v[42:43], v[46:47], v[40:41]
	v_pk_mul_f32 v[40:41], v[44:45], v[54:55]
	v_pk_mul_f32 v[54:55], v[36:37], v[50:51] op_sel_hi:[1,0]
	v_pk_mul_f32 v[36:37], v[36:37], v[32:33]
	v_pk_mul_f32 v[44:45], v[38:39], v[50:51] op_sel_hi:[1,0]
	v_pk_mul_f32 v[38:39], v[38:39], v[34:35]
	v_exp_f32_e32 v54, v54
	v_exp_f32_e32 v55, v55
	v_exp_f32_e32 v44, v44
	v_exp_f32_e32 v45, v45
	v_pk_add_f32 v[54:55], v[54:55], 1.0 op_sel_hi:[1,0]
	v_pk_add_f32 v[44:45], v[44:45], 1.0 op_sel_hi:[1,0]
	v_rcp_f32_e32 v54, v54
	v_rcp_f32_e32 v55, v55
	v_rcp_f32_e32 v44, v44
	v_rcp_f32_e32 v45, v45
	v_pk_mul_f32 v[54:55], v[54:55], v[50:51] op_sel:[0,1]
	v_pk_mul_f32 v[44:45], v[44:45], v[50:51] op_sel:[0,1]
	v_pk_mul_f32 v[36:37], v[36:37], v[54:55]
	v_pk_mul_f32 v[38:39], v[38:39], v[44:45]
	v_cvt_pk_bf16_f32 v34, v36, v37
	v_cvt_pk_bf16_f32 v32, v40, v41
	v_cvt_pk_bf16_f32 v33, v42, v43
	v_cvt_pk_bf16_f32 v35, v38, v39
	v_mad_u32_u24 v36, v48, s16, v96
	global_store_dwordx4 v36, v[32:35], s[6:7] sc1
	s_nop 1
	v_add_u32_e32 v32, 0xa0, v130
	s_waitcnt vmcnt(7)
	v_add_f32_e32 v33, v160, v161
	v_add_f32_e32 v34, v162, v163
	v_add_f32_e32 v33, v33, v34
	v_mov_b32_e32 v34, v33
	s_nop 1
	v_permlane16_swap_b32_e32 v33, v34
	v_add_f32_e32 v33, v33, v34
	v_mov_b32_e32 v34, v33
	s_nop 1
	v_permlane32_swap_b32_e32 v33, v34
	v_add_f32_e32 v33, v33, v34
	v_fmamk_f32 v33, v33, 0x3a800000, v225
	v_rsq_f32_e32 v34, v33
	s_nop 0
	v_mul_f32_e32 v35, v34, v34
	v_mul_f32_e32 v34, 0xbfb8aa3b, v34
	v_pk_mul_f32 v[36:37], v[28:29], v[34:35] op_sel_hi:[1,0]
	v_pk_mul_f32 v[28:29], v[28:29], v[24:25]
	v_pk_mul_f32 v[24:25], v[30:31], v[34:35] op_sel_hi:[1,0]
	v_pk_mul_f32 v[30:31], v[30:31], v[26:27]
	v_exp_f32_e32 v36, v36
	v_exp_f32_e32 v37, v37
	v_exp_f32_e32 v24, v24
	v_exp_f32_e32 v25, v25
	v_pk_add_f32 v[36:37], v[36:37], 1.0 op_sel_hi:[1,0]
	v_pk_add_f32 v[24:25], v[24:25], 1.0 op_sel_hi:[1,0]
	v_rcp_f32_e32 v36, v36
	v_rcp_f32_e32 v37, v37
	v_rcp_f32_e32 v24, v24
	v_rcp_f32_e32 v25, v25
	v_pk_mul_f32 v[36:37], v[36:37], v[34:35] op_sel:[0,1]
	v_pk_mul_f32 v[24:25], v[24:25], v[34:35] op_sel:[0,1]
	s_nop 0
	v_pk_mul_f32 v[26:27], v[30:31], v[24:25]
	v_pk_mul_f32 v[24:25], v[28:29], v[36:37]
	v_pk_mul_f32 v[36:37], v[20:21], v[34:35] op_sel_hi:[1,0]
	v_pk_mul_f32 v[20:21], v[20:21], v[16:17]
	v_pk_mul_f32 v[28:29], v[22:23], v[34:35] op_sel_hi:[1,0]
	v_pk_mul_f32 v[22:23], v[22:23], v[18:19]
	v_exp_f32_e32 v36, v36
	v_exp_f32_e32 v37, v37
	v_exp_f32_e32 v28, v28
	v_exp_f32_e32 v29, v29
	v_pk_add_f32 v[36:37], v[36:37], 1.0 op_sel_hi:[1,0]
	v_pk_add_f32 v[28:29], v[28:29], 1.0 op_sel_hi:[1,0]
	v_rcp_f32_e32 v36, v36
	v_rcp_f32_e32 v37, v37
	v_rcp_f32_e32 v28, v28
	v_rcp_f32_e32 v29, v29
	v_pk_mul_f32 v[36:37], v[36:37], v[34:35] op_sel:[0,1]
	v_pk_mul_f32 v[28:29], v[28:29], v[34:35] op_sel:[0,1]
	v_pk_mul_f32 v[20:21], v[20:21], v[36:37]
	v_pk_mul_f32 v[22:23], v[22:23], v[28:29]
	v_cvt_pk_bf16_f32 v18, v20, v21
	v_cvt_pk_bf16_f32 v16, v24, v25
	v_cvt_pk_bf16_f32 v17, v26, v27
	v_cvt_pk_bf16_f32 v19, v22, v23
	v_mad_u32_u24 v20, v32, s16, v96
	global_store_dwordx4 v20, v[16:19], s[6:7] sc1
	s_nop 1
	v_add_u32_e32 v16, 0xb0, v130
	s_waitcnt vmcnt(7)
	v_add_f32_e32 v17, v164, v165
	v_add_f32_e32 v18, v166, v167
	v_add_f32_e32 v17, v17, v18
	v_mov_b32_e32 v18, v17
	s_nop 1
	v_permlane16_swap_b32_e32 v17, v18
	v_add_f32_e32 v17, v17, v18
	v_mov_b32_e32 v18, v17
	s_nop 1
	v_permlane32_swap_b32_e32 v17, v18
	v_add_f32_e32 v17, v17, v18
	v_fmamk_f32 v17, v17, 0x3a800000, v225
	v_rsq_f32_e32 v18, v17
	s_nop 0
	v_mul_f32_e32 v19, v18, v18
	v_mul_f32_e32 v18, 0xbfb8aa3b, v18
	v_pk_mul_f32 v[20:21], v[12:13], v[18:19] op_sel_hi:[1,0]
	v_pk_mul_f32 v[12:13], v[12:13], v[8:9]
	v_pk_mul_f32 v[8:9], v[14:15], v[18:19] op_sel_hi:[1,0]
	v_pk_mul_f32 v[14:15], v[14:15], v[10:11]
	v_exp_f32_e32 v20, v20
	v_exp_f32_e32 v21, v21
	v_exp_f32_e32 v8, v8
	v_exp_f32_e32 v9, v9
	v_pk_add_f32 v[20:21], v[20:21], 1.0 op_sel_hi:[1,0]
	v_pk_add_f32 v[8:9], v[8:9], 1.0 op_sel_hi:[1,0]
	v_rcp_f32_e32 v20, v20
	v_rcp_f32_e32 v21, v21
	v_rcp_f32_e32 v8, v8
	v_rcp_f32_e32 v9, v9
	v_pk_mul_f32 v[20:21], v[20:21], v[18:19] op_sel:[0,1]
	v_pk_mul_f32 v[8:9], v[8:9], v[18:19] op_sel:[0,1]
	s_nop 0
	v_pk_mul_f32 v[10:11], v[14:15], v[8:9]
	v_pk_mul_f32 v[8:9], v[12:13], v[20:21]
	v_pk_mul_f32 v[20:21], v[4:5], v[18:19] op_sel_hi:[1,0]
	v_pk_mul_f32 v[4:5], v[4:5], v[0:1]
	v_pk_mul_f32 v[12:13], v[6:7], v[18:19] op_sel_hi:[1,0]
	v_pk_mul_f32 v[6:7], v[6:7], v[2:3]
	v_exp_f32_e32 v20, v20
	v_exp_f32_e32 v21, v21
	v_exp_f32_e32 v12, v12
	v_exp_f32_e32 v13, v13
	v_pk_add_f32 v[20:21], v[20:21], 1.0 op_sel_hi:[1,0]
	v_pk_add_f32 v[12:13], v[12:13], 1.0 op_sel_hi:[1,0]
	v_rcp_f32_e32 v20, v20
	v_rcp_f32_e32 v21, v21
	v_rcp_f32_e32 v12, v12
	v_rcp_f32_e32 v13, v13
	v_pk_mul_f32 v[20:21], v[20:21], v[18:19] op_sel:[0,1]
	v_pk_mul_f32 v[12:13], v[12:13], v[18:19] op_sel:[0,1]
	v_pk_mul_f32 v[4:5], v[4:5], v[20:21]
	v_pk_mul_f32 v[6:7], v[6:7], v[12:13]
	v_cvt_pk_bf16_f32 v2, v4, v5
	v_cvt_pk_bf16_f32 v0, v8, v9
	v_cvt_pk_bf16_f32 v1, v10, v11
	v_cvt_pk_bf16_f32 v3, v6, v7
	v_mad_u32_u24 v4, v16, s16, v96
	global_store_dwordx4 v4, v[0:3], s[6:7] sc1
	s_and_b64 vcc, exec, s[36:37]
	s_mov_b64 s[30:31], -1
	s_cbranch_vccnz .LBB0_349

.LBB0_443:
	v_pk_mul_f32 v[130:131], v[130:131], v[96:97] op_sel_hi:[1,0]
	v_pk_mul_f32 v[128:129], v[128:129], v[96:97] op_sel_hi:[1,0]
	v_pk_mul_f32 v[126:127], v[126:127], v[96:97] op_sel_hi:[1,0]
	v_pk_mul_f32 v[124:125], v[124:125], v[96:97] op_sel_hi:[1,0]
	v_pk_mul_f32 v[122:123], v[122:123], v[96:97] op_sel_hi:[1,0]
	v_pk_mul_f32 v[120:121], v[120:121], v[96:97] op_sel_hi:[1,0]
	v_pk_mul_f32 v[118:119], v[118:119], v[96:97] op_sel_hi:[1,0]
	v_pk_mul_f32 v[116:117], v[116:117], v[96:97] op_sel_hi:[1,0]
	s_and_saveexec_b64 s[30:31], s[64:65]
	s_cbranch_execz .LBB0_445
	s_waitcnt vmcnt(2)
	v_mov_b32_e32 v138, v192
	v_mov_b32_e32 v139, v193
	v_mov_b32_e32 v140, v194
	v_mov_b32_e32 v141, v195
	v_mov_b32_e32 v142, v158
	v_mov_b32_e32 v143, v159
	v_mov_b32_e32 v144, v160
	v_mov_b32_e32 v145, v161
	v_lshlrev_b32_e32 v192, 7, v132
	v_add_u32_e32 v192, 0x1000, v192
	v_mov_b32_e32 v158, v192
	global_load_dwordx4 v[192:195], v192, s[72:73] offset:16
	global_load_dwordx4 v[158:161], v158, s[72:73]
	v_mul_f32_e32 v150, v126, v139
	v_mul_f32_e32 v152, v126, v138
	v_mov_b32_e32 v126, v131
	v_mul_f32_e32 v148, v130, v138
	v_mul_f32_e32 v154, v130, v139
	v_pk_mul_f32 v[156:157], v[126:127], v[140:141]
	v_mov_b32_e32 v130, v127
	v_mov_b32_e32 v149, v156
	v_mov_b32_e32 v151, v157
	v_pk_mul_f32 v[126:127], v[130:131], v[140:141]
	v_mov_b32_e32 v146, v142
	v_mov_b32_e32 v147, v144
	v_mov_b32_e32 v144, v143
	v_pk_add_f32 v[148:149], v[148:149], v[150:151] neg_lo:[0,1] neg_hi:[0,1]
	v_mov_b32_e32 v155, v127
	v_mov_b32_e32 v153, v126
	v_mul_f32_e32 v130, v122, v138
	v_mul_f32_e32 v150, v118, v139
	v_mul_f32_e32 v138, v118, v138
	v_mov_b32_e32 v118, v123
	v_pk_mul_f32 v[142:143], v[124:125], v[144:145]
	v_pk_mul_f32 v[124:125], v[124:125], v[146:147]
	v_pk_add_f32 v[126:127], v[154:155], v[152:153]
	v_mul_f32_e32 v152, v122, v139
	v_pk_mul_f32 v[154:155], v[118:119], v[140:141]
	v_mov_b32_e32 v122, v119
	v_pk_fma_f32 v[142:143], v[128:129], v[146:147], v[142:143] neg_lo:[0,0,1] neg_hi:[0,0,1]
	v_pk_fma_f32 v[124:125], v[128:129], v[144:145], v[124:125]
	v_pk_mul_f32 v[128:129], v[116:117], v[144:145]
	v_mov_b32_e32 v131, v154
	v_mov_b32_e32 v151, v155
	v_pk_mul_f32 v[118:119], v[122:123], v[140:141]
	v_pk_mul_f32 v[116:117], v[116:117], v[146:147]
	v_pk_fma_f32 v[128:129], v[120:121], v[146:147], v[128:129] neg_lo:[0,0,1] neg_hi:[0,0,1]
	v_pk_add_f32 v[130:131], v[130:131], v[150:151] neg_lo:[0,1] neg_hi:[0,1]
	v_mov_b32_e32 v153, v119
	v_mov_b32_e32 v139, v118
	v_pk_fma_f32 v[116:117], v[120:121], v[144:145], v[116:117]
	v_pk_add_f32 v[118:119], v[152:153], v[138:139]
	v_mov_b32_e32 v120, v128
	v_mov_b32_e32 v121, v129
	v_mov_b32_e32 v122, v130
	v_mov_b32_e32 v123, v131
	v_mov_b32_e32 v128, v142
	v_mov_b32_e32 v129, v143
	v_mov_b32_e32 v130, v148
	v_mov_b32_e32 v131, v149

.LBB0_450:
	v_pk_mul_f32 v[114:115], v[114:115], v[96:97] op_sel_hi:[1,0]
	v_pk_mul_f32 v[112:113], v[112:113], v[96:97] op_sel_hi:[1,0]
	v_pk_mul_f32 v[110:111], v[110:111], v[96:97] op_sel_hi:[1,0]
	v_pk_mul_f32 v[108:109], v[108:109], v[96:97] op_sel_hi:[1,0]
	v_pk_mul_f32 v[106:107], v[106:107], v[96:97] op_sel_hi:[1,0]
	v_pk_mul_f32 v[104:105], v[104:105], v[96:97] op_sel_hi:[1,0]
	v_pk_mul_f32 v[102:103], v[102:103], v[96:97] op_sel_hi:[1,0]
	v_pk_mul_f32 v[100:101], v[100:101], v[96:97] op_sel_hi:[1,0]
	s_and_saveexec_b64 s[30:31], s[64:65]
	s_cbranch_execz .LBB0_452
	s_waitcnt vmcnt(2)
	v_mov_b32_e32 v118, v192
	v_mov_b32_e32 v119, v193
	v_mov_b32_e32 v120, v194
	v_mov_b32_e32 v121, v195
	v_mov_b32_e32 v122, v158
	v_mov_b32_e32 v123, v159
	v_mov_b32_e32 v124, v160
	v_mov_b32_e32 v125, v161
	v_lshlrev_b32_e32 v192, 7, v132
	v_add_u32_e32 v192, 0x1800, v192
	v_mov_b32_e32 v158, v192
	global_load_dwordx4 v[192:195], v192, s[72:73] offset:16
	global_load_dwordx4 v[158:161], v158, s[72:73]
	v_mul_f32_e32 v130, v110, v119
	v_mul_f32_e32 v136, v110, v118
	v_mov_b32_e32 v110, v115
	v_mul_f32_e32 v128, v114, v118
	v_mul_f32_e32 v138, v114, v119
	v_pk_mul_f32 v[140:141], v[110:111], v[120:121]
	v_mov_b32_e32 v114, v111
	v_mov_b32_e32 v129, v140
	v_mov_b32_e32 v131, v141
	v_pk_mul_f32 v[110:111], v[114:115], v[120:121]
	v_mov_b32_e32 v126, v122
	v_mov_b32_e32 v127, v124
	v_mov_b32_e32 v124, v123
	v_pk_add_f32 v[128:129], v[128:129], v[130:131] neg_lo:[0,1] neg_hi:[0,1]
	v_mov_b32_e32 v139, v111
	v_mov_b32_e32 v137, v110
	v_mul_f32_e32 v114, v106, v118
	v_mul_f32_e32 v130, v102, v119
	v_mul_f32_e32 v118, v102, v118
	v_mov_b32_e32 v102, v107
	v_pk_mul_f32 v[122:123], v[108:109], v[124:125]
	v_pk_mul_f32 v[108:109], v[108:109], v[126:127]
	v_pk_add_f32 v[110:111], v[138:139], v[136:137]
	v_mul_f32_e32 v136, v106, v119
	v_pk_mul_f32 v[138:139], v[102:103], v[120:121]
	v_mov_b32_e32 v106, v103
	v_pk_fma_f32 v[122:123], v[112:113], v[126:127], v[122:123] neg_lo:[0,0,1] neg_hi:[0,0,1]
	v_pk_fma_f32 v[108:109], v[112:113], v[124:125], v[108:109]
	v_pk_mul_f32 v[112:113], v[100:101], v[124:125]
	v_mov_b32_e32 v115, v138
	v_mov_b32_e32 v131, v139
	v_pk_mul_f32 v[102:103], v[106:107], v[120:121]
	v_pk_mul_f32 v[100:101], v[100:101], v[126:127]
	v_pk_fma_f32 v[112:113], v[104:105], v[126:127], v[112:113] neg_lo:[0,0,1] neg_hi:[0,0,1]
	v_pk_add_f32 v[114:115], v[114:115], v[130:131] neg_lo:[0,1] neg_hi:[0,1]
	v_mov_b32_e32 v137, v103
	v_mov_b32_e32 v119, v102
	v_pk_fma_f32 v[100:101], v[104:105], v[124:125], v[100:101]
	v_pk_add_f32 v[102:103], v[136:137], v[118:119]
	v_mov_b32_e32 v104, v112
	v_mov_b32_e32 v105, v113
	v_mov_b32_e32 v106, v114
	v_mov_b32_e32 v107, v115
	v_mov_b32_e32 v112, v122
	v_mov_b32_e32 v113, v123
	v_mov_b32_e32 v114, v128
	v_mov_b32_e32 v115, v129

.LBB0_457:
	v_pk_mul_f32 v[94:95], v[94:95], v[96:97] op_sel_hi:[1,0]
	v_pk_mul_f32 v[92:93], v[92:93], v[96:97] op_sel_hi:[1,0]
	v_pk_mul_f32 v[90:91], v[90:91], v[96:97] op_sel_hi:[1,0]
	v_pk_mul_f32 v[88:89], v[88:89], v[96:97] op_sel_hi:[1,0]
	v_pk_mul_f32 v[86:87], v[86:87], v[96:97] op_sel_hi:[1,0]
	v_pk_mul_f32 v[84:85], v[84:85], v[96:97] op_sel_hi:[1,0]
	v_pk_mul_f32 v[82:83], v[82:83], v[96:97] op_sel_hi:[1,0]
	v_pk_mul_f32 v[80:81], v[80:81], v[96:97] op_sel_hi:[1,0]
	s_and_saveexec_b64 s[30:31], s[64:65]
	s_cbranch_execz .LBB0_459
	s_waitcnt vmcnt(2)
	v_mov_b32_e32 v102, v192
	v_mov_b32_e32 v103, v193
	v_mov_b32_e32 v104, v194
	v_mov_b32_e32 v105, v195
	v_mov_b32_e32 v106, v158
	v_mov_b32_e32 v107, v159
	v_mov_b32_e32 v108, v160
	v_mov_b32_e32 v109, v161
	v_lshlrev_b32_e32 v192, 7, v132
	v_add_u32_e32 v192, 0x4000, v192
	v_mov_b32_e32 v158, v192
	global_load_dwordx4 v[192:195], v192, s[72:73] offset:16
	global_load_dwordx4 v[158:161], v158, s[72:73]
	v_mul_f32_e32 v114, v90, v103
	v_mul_f32_e32 v116, v90, v102
	v_mov_b32_e32 v90, v95
	v_mul_f32_e32 v112, v94, v102
	v_mul_f32_e32 v118, v94, v103
	v_pk_mul_f32 v[120:121], v[90:91], v[104:105]
	v_mov_b32_e32 v94, v91
	v_mov_b32_e32 v113, v120
	v_mov_b32_e32 v115, v121
	v_pk_mul_f32 v[90:91], v[94:95], v[104:105]
	v_mov_b32_e32 v110, v106
	v_mov_b32_e32 v111, v108
	v_mov_b32_e32 v108, v107
	v_pk_add_f32 v[112:113], v[112:113], v[114:115] neg_lo:[0,1] neg_hi:[0,1]
	v_mov_b32_e32 v119, v91
	v_mov_b32_e32 v117, v90
	v_mul_f32_e32 v94, v86, v102
	v_mul_f32_e32 v114, v82, v103
	v_mul_f32_e32 v102, v82, v102
	v_mov_b32_e32 v82, v87
	v_pk_mul_f32 v[106:107], v[88:89], v[108:109]
	v_pk_mul_f32 v[88:89], v[88:89], v[110:111]
	v_pk_add_f32 v[90:91], v[118:119], v[116:117]
	v_mul_f32_e32 v116, v86, v103
	v_pk_mul_f32 v[118:119], v[82:83], v[104:105]
	v_mov_b32_e32 v86, v83
	v_pk_fma_f32 v[106:107], v[92:93], v[110:111], v[106:107] neg_lo:[0,0,1] neg_hi:[0,0,1]
	v_pk_fma_f32 v[88:89], v[92:93], v[108:109], v[88:89]
	v_pk_mul_f32 v[92:93], v[80:81], v[108:109]
	v_mov_b32_e32 v95, v118
	v_mov_b32_e32 v115, v119
	v_pk_mul_f32 v[82:83], v[86:87], v[104:105]
	v_pk_mul_f32 v[80:81], v[80:81], v[110:111]
	v_pk_fma_f32 v[92:93], v[84:85], v[110:111], v[92:93] neg_lo:[0,0,1] neg_hi:[0,0,1]
	v_pk_add_f32 v[94:95], v[94:95], v[114:115] neg_lo:[0,1] neg_hi:[0,1]
	v_mov_b32_e32 v117, v83
	v_mov_b32_e32 v103, v82
	v_pk_fma_f32 v[80:81], v[84:85], v[108:109], v[80:81]
	v_pk_add_f32 v[82:83], v[116:117], v[102:103]
	v_mov_b32_e32 v84, v92
	v_mov_b32_e32 v85, v93
	v_mov_b32_e32 v86, v94
	v_mov_b32_e32 v87, v95
	v_mov_b32_e32 v92, v106
	v_mov_b32_e32 v93, v107
	v_mov_b32_e32 v94, v112
	v_mov_b32_e32 v95, v113

.LBB0_461:
	v_mad_u64_u32 v[102:103], s[30:31], v100, s93, 0
	v_mov_b32_e32 v96, v103
	v_mad_u64_u32 v[100:101], s[30:31], v101, s93, v[96:97]
	v_mov_b32_e32 v103, v100
	v_cvt_pk_bf16_f32 v84, v84, v85
	v_cvt_pk_bf16_f32 v85, v86, v87
	v_cvt_pk_bf16_f32 v86, v80, v81
	v_add_u32_e32 v80, 0x80, v132
	v_lshl_add_u64 v[100:101], v[102:103], 1, v[134:135]
	v_cvt_pk_bf16_f32 v92, v92, v93
	v_cvt_pk_bf16_f32 v93, v94, v95
	v_cvt_pk_bf16_f32 v94, v88, v89
	v_cvt_pk_bf16_f32 v95, v90, v91
	v_cvt_pk_bf16_f32 v87, v82, v83
	s_and_b64 vcc, exec, s[44:45]
	v_ashrrev_i32_e32 v81, 31, v80
	global_store_dwordx4 v[100:101], v[92:95], off sc1
	global_store_dwordx4 v[100:101], v[84:87], off offset:256 sc1
	s_cbranch_vccnz .LBB0_463
	s_waitcnt vmcnt(7)
	v_add_f32_e32 v82, v174, v175
	v_add_f32_e32 v83, v176, v177
	v_add_f32_e32 v82, v82, v83
	v_mov_b32_e32 v83, v82
	s_nop 1
	v_permlane16_swap_b32_e32 v82, v83
	v_add_f32_e32 v82, v82, v83
	v_mov_b32_e32 v83, v82
	s_nop 1
	v_permlane32_swap_b32_e32 v82, v83
	v_add_f32_e32 v82, v82, v83
	v_fmamk_f32 v82, v82, 0x3a800000, v225
	v_rsq_f32_e32 v86, v82
	s_nop 0
	s_branch .LBB0_464

.LBB0_464:
	v_pk_mul_f32 v[84:85], v[66:67], v[86:87] op_sel_hi:[1,0]
	v_pk_mul_f32 v[82:83], v[64:65], v[86:87] op_sel_hi:[1,0]
	v_pk_mul_f32 v[64:65], v[78:79], v[86:87] op_sel_hi:[1,0]
	v_pk_mul_f32 v[76:77], v[76:77], v[86:87] op_sel_hi:[1,0]
	v_pk_mul_f32 v[74:75], v[74:75], v[86:87] op_sel_hi:[1,0]
	v_pk_mul_f32 v[66:67], v[72:73], v[86:87] op_sel_hi:[1,0]
	v_pk_mul_f32 v[70:71], v[70:71], v[86:87] op_sel_hi:[1,0]
	v_pk_mul_f32 v[68:69], v[68:69], v[86:87] op_sel_hi:[1,0]
	s_and_saveexec_b64 s[30:31], s[64:65]
	s_cbranch_execz .LBB0_466
	s_waitcnt vmcnt(2)
	v_mov_b32_e32 v86, v192
	v_mov_b32_e32 v87, v193
	v_mov_b32_e32 v88, v194
	v_mov_b32_e32 v89, v195
	v_mov_b32_e32 v90, v158
	v_mov_b32_e32 v91, v159
	v_mov_b32_e32 v92, v160
	v_mov_b32_e32 v93, v161
	v_lshlrev_b32_e32 v192, 7, v132
	v_add_u32_e32 v192, 0x4800, v192
	v_mov_b32_e32 v158, v192
	global_load_dwordx4 v[192:195], v192, s[72:73] offset:16
	global_load_dwordx4 v[158:161], v158, s[72:73]
	v_mul_f32_e32 v94, v64, v87
	v_mul_f32_e32 v100, v64, v86
	v_mov_b32_e32 v64, v85
	v_mov_b32_e32 v72, v90
	v_mul_f32_e32 v90, v84, v86
	v_mul_f32_e32 v102, v84, v87
	v_pk_mul_f32 v[104:105], v[64:65], v[88:89]
	v_mov_b32_e32 v84, v65
	v_mov_b32_e32 v73, v92
	v_mov_b32_e32 v92, v91
	v_mov_b32_e32 v91, v104
	v_mov_b32_e32 v95, v105
	v_pk_mul_f32 v[64:65], v[84:85], v[88:89]
	v_pk_add_f32 v[90:91], v[90:91], v[94:95] neg_lo:[0,1] neg_hi:[0,1]
	v_mov_b32_e32 v103, v65
	v_mov_b32_e32 v101, v64
	v_mul_f32_e32 v84, v74, v86
	v_mul_f32_e32 v94, v70, v87
	v_mul_f32_e32 v86, v70, v86
	v_mov_b32_e32 v70, v75
	v_pk_mul_f32 v[78:79], v[76:77], v[92:93]
	v_pk_mul_f32 v[76:77], v[76:77], v[72:73]
	v_pk_add_f32 v[64:65], v[102:103], v[100:101]
	v_mul_f32_e32 v100, v74, v87
	v_pk_mul_f32 v[102:103], v[70:71], v[88:89]
	v_mov_b32_e32 v74, v71
	v_pk_fma_f32 v[78:79], v[82:83], v[72:73], v[78:79] neg_lo:[0,0,1] neg_hi:[0,0,1]
	v_pk_fma_f32 v[76:77], v[82:83], v[92:93], v[76:77]
	v_pk_mul_f32 v[82:83], v[68:69], v[92:93]
	v_mov_b32_e32 v85, v102
	v_mov_b32_e32 v95, v103
	v_pk_mul_f32 v[70:71], v[74:75], v[88:89]
	v_pk_mul_f32 v[68:69], v[68:69], v[72:73]
	v_pk_fma_f32 v[72:73], v[66:67], v[72:73], v[82:83] neg_lo:[0,0,1] neg_hi:[0,0,1]
	v_pk_add_f32 v[82:83], v[84:85], v[94:95] neg_lo:[0,1] neg_hi:[0,1]
	v_mov_b32_e32 v101, v71
	v_mov_b32_e32 v87, v70
	v_pk_fma_f32 v[68:69], v[66:67], v[92:93], v[68:69]
	v_pk_add_f32 v[70:71], v[100:101], v[86:87]
	v_mov_b32_e32 v66, v72
	v_mov_b32_e32 v67, v73
	v_mov_b32_e32 v74, v82
	v_mov_b32_e32 v75, v83
	v_mov_b32_e32 v82, v78
	v_mov_b32_e32 v83, v79
	v_mov_b32_e32 v84, v90
	v_mov_b32_e32 v85, v91

.LBB0_468:
	v_mad_u64_u32 v[72:73], s[30:31], v80, s93, 0
	v_mov_b32_e32 v78, v73
	v_mad_u64_u32 v[78:79], s[30:31], v81, s93, v[78:79]
	v_mov_b32_e32 v73, v78
	v_lshl_add_u64 v[72:73], v[72:73], 1, v[134:135]
	v_cvt_pk_bf16_f32 v81, v64, v65
	v_cvt_pk_bf16_f32 v64, v66, v67
	v_cvt_pk_bf16_f32 v65, v74, v75
	v_cvt_pk_bf16_f32 v66, v68, v69
	v_cvt_pk_bf16_f32 v67, v70, v71
	global_store_dwordx4 v[72:73], v[64:67], off offset:256 sc1
	v_cvt_pk_bf16_f32 v78, v82, v83
	v_cvt_pk_bf16_f32 v79, v84, v85
	v_add_u32_e32 v64, 0x90, v132
	v_cvt_pk_bf16_f32 v80, v76, v77
	s_and_b64 vcc, exec, s[44:45]
	v_ashrrev_i32_e32 v65, 31, v64
	global_store_dwordx4 v[72:73], v[78:81], off sc1
	s_cbranch_vccnz .LBB0_470
	s_waitcnt vmcnt(7)
	v_add_f32_e32 v66, v178, v179
	v_add_f32_e32 v67, v180, v181
	v_add_f32_e32 v66, v66, v67
	v_mov_b32_e32 v67, v66
	s_nop 1
	v_permlane16_swap_b32_e32 v66, v67
	v_add_f32_e32 v66, v66, v67
	v_mov_b32_e32 v67, v66
	s_nop 1
	v_permlane32_swap_b32_e32 v66, v67
	v_add_f32_e32 v66, v66, v67
	v_fmamk_f32 v66, v66, 0x3a800000, v225
	v_rsq_f32_e32 v66, v66
	s_nop 0
	s_branch .LBB0_471

.LBB0_471:
	v_pk_mul_f32 v[58:59], v[58:59], v[66:67] op_sel_hi:[1,0]
	v_pk_mul_f32 v[56:57], v[56:57], v[66:67] op_sel_hi:[1,0]
	v_pk_mul_f32 v[54:55], v[54:55], v[66:67] op_sel_hi:[1,0]
	v_pk_mul_f32 v[52:53], v[52:53], v[66:67] op_sel_hi:[1,0]
	v_pk_mul_f32 v[46:47], v[46:47], v[66:67] op_sel_hi:[1,0]
	v_pk_mul_f32 v[44:45], v[44:45], v[66:67] op_sel_hi:[1,0]
	v_pk_mul_f32 v[42:43], v[42:43], v[66:67] op_sel_hi:[1,0]
	v_pk_mul_f32 v[40:41], v[40:41], v[66:67] op_sel_hi:[1,0]
	s_and_saveexec_b64 s[30:31], s[64:65]
	s_cbranch_execz .LBB0_473
	s_waitcnt vmcnt(2)
	v_mov_b32_e32 v66, v192
	v_mov_b32_e32 v67, v193
	v_mov_b32_e32 v68, v194
	v_mov_b32_e32 v69, v195
	v_mov_b32_e32 v70, v158
	v_mov_b32_e32 v71, v159
	v_mov_b32_e32 v72, v160
	v_mov_b32_e32 v73, v161
	v_lshlrev_b32_e32 v192, 7, v132
	v_add_u32_e32 v192, 0x5000, v192
	v_mov_b32_e32 v158, v192
	global_load_dwordx4 v[192:195], v192, s[72:73] offset:16
	global_load_dwordx4 v[158:161], v158, s[72:73]
	v_mul_f32_e32 v78, v54, v67
	v_mul_f32_e32 v80, v54, v66
	v_mov_b32_e32 v54, v59
	v_mul_f32_e32 v76, v58, v66
	v_mul_f32_e32 v82, v58, v67
	v_pk_mul_f32 v[84:85], v[54:55], v[68:69]
	v_mov_b32_e32 v58, v55
	v_mov_b32_e32 v77, v84
	v_mov_b32_e32 v79, v85
	v_pk_mul_f32 v[54:55], v[58:59], v[68:69]
	v_mov_b32_e32 v74, v70
	v_mov_b32_e32 v75, v72
	v_mov_b32_e32 v72, v71
	v_pk_add_f32 v[76:77], v[76:77], v[78:79] neg_lo:[0,1] neg_hi:[0,1]
	v_mov_b32_e32 v83, v55
	v_mov_b32_e32 v81, v54
	v_mul_f32_e32 v58, v46, v66
	v_mul_f32_e32 v78, v42, v67
	v_mul_f32_e32 v66, v42, v66
	v_mov_b32_e32 v42, v47
	v_pk_mul_f32 v[70:71], v[52:53], v[72:73]
	v_pk_mul_f32 v[52:53], v[52:53], v[74:75]
	v_pk_add_f32 v[54:55], v[82:83], v[80:81]
	v_mul_f32_e32 v80, v46, v67
	v_pk_mul_f32 v[82:83], v[42:43], v[68:69]
	v_mov_b32_e32 v46, v43
	v_pk_fma_f32 v[70:71], v[56:57], v[74:75], v[70:71] neg_lo:[0,0,1] neg_hi:[0,0,1]
	v_pk_fma_f32 v[52:53], v[56:57], v[72:73], v[52:53]
	v_pk_mul_f32 v[56:57], v[40:41], v[72:73]
	v_mov_b32_e32 v59, v82
	v_mov_b32_e32 v79, v83
	v_pk_mul_f32 v[42:43], v[46:47], v[68:69]
	v_pk_mul_f32 v[40:41], v[40:41], v[74:75]
	v_pk_fma_f32 v[56:57], v[44:45], v[74:75], v[56:57] neg_lo:[0,0,1] neg_hi:[0,0,1]
	v_pk_add_f32 v[58:59], v[58:59], v[78:79] neg_lo:[0,1] neg_hi:[0,1]
	v_mov_b32_e32 v81, v43
	v_mov_b32_e32 v67, v42
	v_pk_fma_f32 v[40:41], v[44:45], v[72:73], v[40:41]
	v_pk_add_f32 v[42:43], v[80:81], v[66:67]
	v_mov_b32_e32 v44, v56
	v_mov_b32_e32 v45, v57
	v_mov_b32_e32 v46, v58
	v_mov_b32_e32 v47, v59
	v_mov_b32_e32 v56, v70
	v_mov_b32_e32 v57, v71
	v_mov_b32_e32 v58, v76
	v_mov_b32_e32 v59, v77

.LBB0_475:
	v_mad_u64_u32 v[66:67], s[30:31], v64, s93, 0
	v_mov_b32_e32 v64, v67
	v_mad_u64_u32 v[64:65], s[30:31], v65, s93, v[64:65]
	v_mov_b32_e32 v67, v64
	v_cvt_pk_bf16_f32 v44, v44, v45
	v_cvt_pk_bf16_f32 v45, v46, v47
	v_cvt_pk_bf16_f32 v46, v40, v41
	v_add_u32_e32 v40, 0xa0, v132
	v_lshl_add_u64 v[64:65], v[66:67], 1, v[134:135]
	v_cvt_pk_bf16_f32 v56, v56, v57
	v_cvt_pk_bf16_f32 v57, v58, v59
	v_cvt_pk_bf16_f32 v58, v52, v53
	v_cvt_pk_bf16_f32 v59, v54, v55
	v_cvt_pk_bf16_f32 v47, v42, v43
	s_and_b64 vcc, exec, s[44:45]
	v_ashrrev_i32_e32 v41, 31, v40
	global_store_dwordx4 v[64:65], v[56:59], off sc1
	global_store_dwordx4 v[64:65], v[44:47], off offset:256 sc1
	s_cbranch_vccnz .LBB0_477
	s_waitcnt vmcnt(7)
	v_add_f32_e32 v42, v182, v183
	v_add_f32_e32 v43, v184, v185
	v_add_f32_e32 v42, v42, v43
	v_mov_b32_e32 v43, v42
	s_nop 1
	v_permlane16_swap_b32_e32 v42, v43
	v_add_f32_e32 v42, v42, v43
	v_mov_b32_e32 v43, v42
	s_nop 1
	v_permlane32_swap_b32_e32 v42, v43
	v_add_f32_e32 v42, v42, v43
	v_fmamk_f32 v42, v42, 0x3a800000, v225
	v_rsq_f32_e32 v42, v42
	s_nop 0
	s_branch .LBB0_478

.LBB0_478:
	v_pk_mul_f32 v[30:31], v[30:31], v[42:43] op_sel_hi:[1,0]
	v_pk_mul_f32 v[28:29], v[28:29], v[42:43] op_sel_hi:[1,0]
	v_pk_mul_f32 v[26:27], v[26:27], v[42:43] op_sel_hi:[1,0]
	v_pk_mul_f32 v[24:25], v[24:25], v[42:43] op_sel_hi:[1,0]
	v_pk_mul_f32 v[22:23], v[22:23], v[42:43] op_sel_hi:[1,0]
	v_pk_mul_f32 v[20:21], v[20:21], v[42:43] op_sel_hi:[1,0]
	v_pk_mul_f32 v[18:19], v[18:19], v[42:43] op_sel_hi:[1,0]
	v_pk_mul_f32 v[16:17], v[16:17], v[42:43] op_sel_hi:[1,0]
	s_and_saveexec_b64 s[30:31], s[64:65]
	s_cbranch_execz .LBB0_480
	s_waitcnt vmcnt(2)
	v_mov_b32_e32 v42, v192
	v_mov_b32_e32 v43, v193
	v_mov_b32_e32 v44, v194
	v_mov_b32_e32 v45, v195
	v_mov_b32_e32 v52, v158
	v_mov_b32_e32 v53, v159
	v_mov_b32_e32 v54, v160
	v_mov_b32_e32 v55, v161
	v_lshlrev_b32_e32 v192, 7, v132
	v_add_u32_e32 v192, 0x5800, v192
	v_mov_b32_e32 v158, v192
	global_load_dwordx4 v[192:195], v192, s[72:73] offset:16
	global_load_dwordx4 v[158:161], v158, s[72:73]
	v_mul_f32_e32 v58, v26, v43
	v_mul_f32_e32 v64, v26, v42
	v_mov_b32_e32 v26, v31
	v_mul_f32_e32 v56, v30, v42
	v_mul_f32_e32 v66, v30, v43
	v_pk_mul_f32 v[68:69], v[26:27], v[44:45]
	v_mov_b32_e32 v30, v27
	v_mov_b32_e32 v57, v68
	v_mov_b32_e32 v59, v69
	v_pk_mul_f32 v[26:27], v[30:31], v[44:45]
	v_mov_b32_e32 v46, v52
	v_mov_b32_e32 v47, v54
	v_mov_b32_e32 v54, v53
	v_pk_add_f32 v[56:57], v[56:57], v[58:59] neg_lo:[0,1] neg_hi:[0,1]
	v_mov_b32_e32 v67, v27
	v_mov_b32_e32 v65, v26
	v_mul_f32_e32 v30, v22, v42
	v_mul_f32_e32 v58, v18, v43
	v_mul_f32_e32 v42, v18, v42
	v_mov_b32_e32 v18, v23
	v_pk_mul_f32 v[52:53], v[24:25], v[54:55]
	v_pk_mul_f32 v[24:25], v[24:25], v[46:47]
	v_pk_add_f32 v[26:27], v[66:67], v[64:65]
	v_mul_f32_e32 v64, v22, v43
	v_pk_mul_f32 v[66:67], v[18:19], v[44:45]
	v_mov_b32_e32 v22, v19
	v_pk_fma_f32 v[52:53], v[28:29], v[46:47], v[52:53] neg_lo:[0,0,1] neg_hi:[0,0,1]
	v_pk_fma_f32 v[24:25], v[28:29], v[54:55], v[24:25]
	v_pk_mul_f32 v[28:29], v[16:17], v[54:55]
	v_mov_b32_e32 v31, v66
	v_mov_b32_e32 v59, v67
	v_pk_mul_f32 v[18:19], v[22:23], v[44:45]
	v_pk_mul_f32 v[16:17], v[16:17], v[46:47]
	v_pk_fma_f32 v[28:29], v[20:21], v[46:47], v[28:29] neg_lo:[0,0,1] neg_hi:[0,0,1]
	v_pk_add_f32 v[30:31], v[30:31], v[58:59] neg_lo:[0,1] neg_hi:[0,1]
	v_mov_b32_e32 v65, v19
	v_mov_b32_e32 v43, v18
	v_pk_fma_f32 v[16:17], v[20:21], v[54:55], v[16:17]
	v_pk_add_f32 v[18:19], v[64:65], v[42:43]
	v_mov_b32_e32 v20, v28
	v_mov_b32_e32 v21, v29
	v_mov_b32_e32 v22, v30
	v_mov_b32_e32 v23, v31
	v_mov_b32_e32 v28, v52
	v_mov_b32_e32 v29, v53
	v_mov_b32_e32 v30, v56
	v_mov_b32_e32 v31, v57

.LBB0_482:
	v_mad_u64_u32 v[42:43], s[30:31], v40, s93, 0
	v_mov_b32_e32 v40, v43
	v_mad_u64_u32 v[40:41], s[30:31], v41, s93, v[40:41]
	v_mov_b32_e32 v43, v40
	v_cvt_pk_bf16_f32 v20, v20, v21
	v_cvt_pk_bf16_f32 v21, v22, v23
	v_cvt_pk_bf16_f32 v22, v16, v17
	v_add_u32_e32 v16, 0xb0, v132
	v_lshl_add_u64 v[40:41], v[42:43], 1, v[134:135]
	v_cvt_pk_bf16_f32 v28, v28, v29
	v_cvt_pk_bf16_f32 v29, v30, v31
	v_cvt_pk_bf16_f32 v30, v24, v25
	v_cvt_pk_bf16_f32 v31, v26, v27
	v_cvt_pk_bf16_f32 v23, v18, v19
	s_and_b64 vcc, exec, s[44:45]
	v_ashrrev_i32_e32 v17, 31, v16
	global_store_dwordx4 v[40:41], v[28:31], off sc1
	global_store_dwordx4 v[40:41], v[20:23], off offset:256 sc1
	s_cbranch_vccnz .LBB0_484
	s_waitcnt vmcnt(7)
	v_add_f32_e32 v18, v186, v187
	v_add_f32_e32 v19, v188, v189
	v_add_f32_e32 v18, v18, v19
	v_mov_b32_e32 v19, v18
	s_nop 1
	v_permlane16_swap_b32_e32 v18, v19
	v_add_f32_e32 v18, v18, v19
	v_mov_b32_e32 v19, v18
	s_nop 1
	v_permlane32_swap_b32_e32 v18, v19
	v_add_f32_e32 v18, v18, v19
	v_fmamk_f32 v18, v18, 0x3a800000, v225
	v_rsq_f32_e32 v18, v18
	s_nop 0
	s_branch .LBB0_485

.LBB0_485:
	v_pk_mul_f32 v[14:15], v[14:15], v[18:19] op_sel_hi:[1,0]
	v_pk_mul_f32 v[12:13], v[12:13], v[18:19] op_sel_hi:[1,0]
	v_pk_mul_f32 v[10:11], v[10:11], v[18:19] op_sel_hi:[1,0]
	v_pk_mul_f32 v[8:9], v[8:9], v[18:19] op_sel_hi:[1,0]
	v_pk_mul_f32 v[6:7], v[6:7], v[18:19] op_sel_hi:[1,0]
	v_pk_mul_f32 v[4:5], v[4:5], v[18:19] op_sel_hi:[1,0]
	v_pk_mul_f32 v[2:3], v[2:3], v[18:19] op_sel_hi:[1,0]
	v_pk_mul_f32 v[0:1], v[0:1], v[18:19] op_sel_hi:[1,0]
	s_and_saveexec_b64 s[30:31], s[64:65]
	s_cbranch_execz .LBB0_487
	s_waitcnt vmcnt(2)
	v_mov_b32_e32 v18, v192
	v_mov_b32_e32 v19, v193
	v_mov_b32_e32 v20, v194
	v_mov_b32_e32 v21, v195
	v_mov_b32_e32 v22, v158
	v_mov_b32_e32 v23, v159
	v_mov_b32_e32 v24, v160
	v_mov_b32_e32 v25, v161
	v_mul_f32_e32 v30, v10, v19
	v_mul_f32_e32 v40, v10, v18
	v_mov_b32_e32 v10, v15
	v_mul_f32_e32 v28, v14, v18
	v_mul_f32_e32 v42, v14, v19
	v_pk_mul_f32 v[44:45], v[10:11], v[20:21]
	v_mov_b32_e32 v14, v11
	v_mov_b32_e32 v29, v44
	v_mov_b32_e32 v31, v45
	v_pk_mul_f32 v[10:11], v[14:15], v[20:21]
	v_mov_b32_e32 v26, v22
	v_mov_b32_e32 v27, v24
	v_mov_b32_e32 v24, v23
	v_pk_add_f32 v[28:29], v[28:29], v[30:31] neg_lo:[0,1] neg_hi:[0,1]
	v_mov_b32_e32 v43, v11
	v_mov_b32_e32 v41, v10
	v_mul_f32_e32 v14, v6, v18
	v_mul_f32_e32 v30, v2, v19
	v_mul_f32_e32 v18, v2, v18
	v_mov_b32_e32 v2, v7
	v_pk_mul_f32 v[22:23], v[8:9], v[24:25]
	v_pk_mul_f32 v[8:9], v[8:9], v[26:27]
	v_pk_add_f32 v[10:11], v[42:43], v[40:41]
	v_mul_f32_e32 v40, v6, v19
	v_pk_mul_f32 v[42:43], v[2:3], v[20:21]
	v_mov_b32_e32 v6, v3
	v_pk_fma_f32 v[22:23], v[12:13], v[26:27], v[22:23] neg_lo:[0,0,1] neg_hi:[0,0,1]
	v_pk_fma_f32 v[8:9], v[12:13], v[24:25], v[8:9]
	v_pk_mul_f32 v[12:13], v[0:1], v[24:25]
	v_mov_b32_e32 v15, v42
	v_mov_b32_e32 v31, v43
	v_pk_mul_f32 v[2:3], v[6:7], v[20:21]
	v_pk_mul_f32 v[0:1], v[0:1], v[26:27]
	v_pk_fma_f32 v[12:13], v[4:5], v[26:27], v[12:13] neg_lo:[0,0,1] neg_hi:[0,0,1]
	v_pk_add_f32 v[14:15], v[14:15], v[30:31] neg_lo:[0,1] neg_hi:[0,1]
	v_mov_b32_e32 v41, v3
	v_mov_b32_e32 v19, v2
	v_pk_fma_f32 v[0:1], v[4:5], v[24:25], v[0:1]
	v_pk_add_f32 v[2:3], v[40:41], v[18:19]
	v_mov_b32_e32 v4, v12
	v_mov_b32_e32 v5, v13
	v_mov_b32_e32 v6, v14
	v_mov_b32_e32 v7, v15
	v_mov_b32_e32 v12, v22
	v_mov_b32_e32 v13, v23
	v_mov_b32_e32 v14, v28
	v_mov_b32_e32 v15, v29

.LBB0_546:
	v_or_b32_e32 v118, 16, v130
	v_ashrrev_i32_e32 v119, 31, v118
	s_mov_b64 s[60:61], -1
	s_waitcnt vmcnt(7)
	v_add_f32_e32 v114, v150, v151
	v_add_f32_e32 v115, v152, v153
	v_add_f32_e32 v114, v114, v115
	v_mov_b32_e32 v115, v114
	s_nop 1
	v_permlane16_swap_b32_e32 v114, v115
	v_add_f32_e32 v114, v114, v115
	v_mov_b32_e32 v115, v114
	s_nop 1
	v_permlane32_swap_b32_e32 v114, v115
	v_add_f32_e32 v114, v114, v115
	v_fmamk_f32 v114, v114, 0x3a800000, v225
	v_lshlrev_b64 v[116:117], 11, v[118:119]
	v_rsq_f32_e32 v114, v114
	s_nop 0
	v_cndmask_b32_e64 v115, 0, 1, s[40:41]
	v_cmp_ne_u32_e64 s[38:39], 1, v115
	s_andn2_b64 vcc, exec, s[40:41]
	s_cbranch_vccnz .LBB0_548
	v_lshl_add_u64 v[118:119], s[26:27], 0, v[116:117]
	v_lshl_add_u64 v[118:119], s[68:69], 1, v[118:119]
	s_lshl_b32 s40, s62, 1
	s_mov_b32 s41, s69
	v_lshl_add_u64 v[118:119], v[118:119], 0, s[40:41]
	v_lshl_add_u64 v[122:123], v[118:119], 0, v[96:97]
	v_pk_mul_f32 v[120:121], v[112:113], v[114:115] op_sel_hi:[1,0]
	v_pk_mul_f32 v[118:119], v[110:111], v[114:115] op_sel_hi:[1,0]
	v_pk_mul_f32 v[124:125], v[104:105], v[114:115] op_sel_hi:[1,0]
	v_pk_mul_f32 v[126:127], v[102:103], v[114:115] op_sel_hi:[1,0]
	v_cvt_pk_bf16_f32 v118, v118, v119
	v_cvt_pk_bf16_f32 v119, v120, v121
	v_cvt_pk_bf16_f32 v120, v126, v127
	v_cvt_pk_bf16_f32 v121, v124, v125
	global_store_dwordx4 v[122:123], v[118:121], off sc1
	v_pk_mul_f32 v[124:125], v[100:101], v[114:115] op_sel_hi:[1,0]
	v_pk_mul_f32 v[126:127], v[98:99], v[114:115] op_sel_hi:[1,0]
	v_pk_mul_f32 v[120:121], v[108:109], v[114:115] op_sel_hi:[1,0]
	v_pk_mul_f32 v[118:119], v[106:107], v[114:115] op_sel_hi:[1,0]
	s_mov_b64 s[60:61], 0
	v_cvt_pk_bf16_f32 v118, v118, v119
	v_cvt_pk_bf16_f32 v119, v120, v121
	v_cvt_pk_bf16_f32 v120, v126, v127
	v_cvt_pk_bf16_f32 v121, v124, v125
	global_store_dwordx4 v[122:123], v[118:121], off offset:256 sc1

.LBB0_550:
	v_or_b32_e32 v102, 32, v130
	v_ashrrev_i32_e32 v103, 31, v102
	s_mov_b64 s[40:41], -1
	s_waitcnt vmcnt(7)
	v_add_f32_e32 v98, v154, v155
	v_add_f32_e32 v99, v156, v157
	v_add_f32_e32 v98, v98, v99
	v_mov_b32_e32 v99, v98
	s_nop 1
	v_permlane16_swap_b32_e32 v98, v99
	v_add_f32_e32 v98, v98, v99
	v_mov_b32_e32 v99, v98
	s_nop 1
	v_permlane32_swap_b32_e32 v98, v99
	v_add_f32_e32 v98, v98, v99
	v_fmamk_f32 v98, v98, 0x3a800000, v225
	v_rsq_f32_e32 v100, v98
	s_nop 0
	s_and_b64 vcc, exec, s[38:39]
	v_lshlrev_b64 v[98:99], 11, v[102:103]
	s_cbranch_vccnz .LBB0_552
	v_lshl_add_u64 v[102:103], s[26:27], 0, v[98:99]
	v_lshl_add_u64 v[102:103], s[68:69], 1, v[102:103]
	s_lshl_b32 s40, s62, 1
	s_mov_b32 s41, s69
	v_lshl_add_u64 v[102:103], v[102:103], 0, s[40:41]
	v_lshl_add_u64 v[106:107], v[102:103], 0, v[96:97]
	v_pk_mul_f32 v[104:105], v[94:95], v[100:101] op_sel_hi:[1,0]
	v_pk_mul_f32 v[102:103], v[92:93], v[100:101] op_sel_hi:[1,0]
	v_pk_mul_f32 v[108:109], v[86:87], v[100:101] op_sel_hi:[1,0]
	v_pk_mul_f32 v[110:111], v[84:85], v[100:101] op_sel_hi:[1,0]
	v_cvt_pk_bf16_f32 v102, v102, v103
	v_cvt_pk_bf16_f32 v103, v104, v105
	v_cvt_pk_bf16_f32 v104, v110, v111
	v_cvt_pk_bf16_f32 v105, v108, v109
	global_store_dwordx4 v[106:107], v[102:105], off sc1
	v_pk_mul_f32 v[108:109], v[82:83], v[100:101] op_sel_hi:[1,0]
	v_pk_mul_f32 v[110:111], v[80:81], v[100:101] op_sel_hi:[1,0]
	v_pk_mul_f32 v[104:105], v[90:91], v[100:101] op_sel_hi:[1,0]
	v_pk_mul_f32 v[102:103], v[88:89], v[100:101] op_sel_hi:[1,0]
	s_mov_b64 s[40:41], 0
	v_cvt_pk_bf16_f32 v102, v102, v103
	v_cvt_pk_bf16_f32 v103, v104, v105
	v_cvt_pk_bf16_f32 v104, v110, v111
	v_cvt_pk_bf16_f32 v105, v108, v109
	global_store_dwordx4 v[106:107], v[102:105], off offset:256 sc1

.LBB0_554:
	v_or_b32_e32 v84, 48, v130
	v_ashrrev_i32_e32 v85, 31, v84
	s_mov_b64 s[40:41], -1
	s_waitcnt vmcnt(7)
	v_add_f32_e32 v80, v158, v159
	v_add_f32_e32 v81, v160, v161
	v_add_f32_e32 v80, v80, v81
	v_mov_b32_e32 v81, v80
	s_nop 1
	v_permlane16_swap_b32_e32 v80, v81
	v_add_f32_e32 v80, v80, v81
	v_mov_b32_e32 v81, v80
	s_nop 1
	v_permlane32_swap_b32_e32 v80, v81
	v_add_f32_e32 v80, v80, v81
	v_fmamk_f32 v80, v80, 0x3a800000, v225
	v_rsq_f32_e32 v82, v80
	s_nop 0
	s_and_b64 vcc, exec, s[38:39]
	v_lshlrev_b64 v[80:81], 11, v[84:85]
	s_cbranch_vccnz .LBB0_556
	v_lshl_add_u64 v[84:85], s[26:27], 0, v[80:81]
	v_lshl_add_u64 v[84:85], s[68:69], 1, v[84:85]
	s_lshl_b32 s40, s62, 1
	s_mov_b32 s41, s69
	v_lshl_add_u64 v[84:85], v[84:85], 0, s[40:41]
	v_lshl_add_u64 v[88:89], v[84:85], 0, v[96:97]
	v_pk_mul_f32 v[86:87], v[78:79], v[82:83] op_sel_hi:[1,0]
	v_pk_mul_f32 v[84:85], v[76:77], v[82:83] op_sel_hi:[1,0]
	v_pk_mul_f32 v[90:91], v[70:71], v[82:83] op_sel_hi:[1,0]
	v_pk_mul_f32 v[92:93], v[68:69], v[82:83] op_sel_hi:[1,0]
	v_cvt_pk_bf16_f32 v84, v84, v85
	v_cvt_pk_bf16_f32 v85, v86, v87
	v_cvt_pk_bf16_f32 v86, v92, v93
	v_cvt_pk_bf16_f32 v87, v90, v91
	global_store_dwordx4 v[88:89], v[84:87], off sc1
	v_pk_mul_f32 v[90:91], v[66:67], v[82:83] op_sel_hi:[1,0]
	v_pk_mul_f32 v[92:93], v[64:65], v[82:83] op_sel_hi:[1,0]
	v_pk_mul_f32 v[86:87], v[74:75], v[82:83] op_sel_hi:[1,0]
	v_pk_mul_f32 v[84:85], v[72:73], v[82:83] op_sel_hi:[1,0]
	s_mov_b64 s[40:41], 0
	v_cvt_pk_bf16_f32 v84, v84, v85
	v_cvt_pk_bf16_f32 v85, v86, v87
	v_cvt_pk_bf16_f32 v86, v92, v93
	v_cvt_pk_bf16_f32 v87, v90, v91
	global_store_dwordx4 v[88:89], v[84:87], off offset:256 sc1

.LBB0_558:
	v_add_u32_e32 v68, 0x80, v130
	v_ashrrev_i32_e32 v69, 31, v68
	s_mov_b64 s[40:41], -1
	s_waitcnt vmcnt(7)
	v_add_f32_e32 v64, v162, v163
	v_add_f32_e32 v65, v164, v165
	v_add_f32_e32 v64, v64, v65
	v_mov_b32_e32 v65, v64
	s_nop 1
	v_permlane16_swap_b32_e32 v64, v65
	v_add_f32_e32 v64, v64, v65
	v_mov_b32_e32 v65, v64
	s_nop 1
	v_permlane32_swap_b32_e32 v64, v65
	v_add_f32_e32 v64, v64, v65
	v_fmamk_f32 v64, v64, 0x3a800000, v225
	v_rsq_f32_e32 v66, v64
	s_nop 0
	s_and_b64 vcc, exec, s[38:39]
	v_lshlrev_b64 v[64:65], 11, v[68:69]
	s_cbranch_vccnz .LBB0_560
	v_lshl_add_u64 v[68:69], s[26:27], 0, v[64:65]
	v_lshl_add_u64 v[68:69], s[68:69], 1, v[68:69]
	s_lshl_b32 s40, s62, 1
	s_mov_b32 s41, s69
	v_lshl_add_u64 v[68:69], v[68:69], 0, s[40:41]
	v_lshl_add_u64 v[72:73], v[68:69], 0, v[96:97]
	v_pk_mul_f32 v[70:71], v[50:51], v[66:67] op_sel_hi:[1,0]
	v_pk_mul_f32 v[68:69], v[48:49], v[66:67] op_sel_hi:[1,0]
	v_pk_mul_f32 v[74:75], v[58:59], v[66:67] op_sel_hi:[1,0]
	v_pk_mul_f32 v[76:77], v[56:57], v[66:67] op_sel_hi:[1,0]
	v_cvt_pk_bf16_f32 v68, v68, v69
	v_cvt_pk_bf16_f32 v69, v70, v71
	v_cvt_pk_bf16_f32 v70, v76, v77
	v_cvt_pk_bf16_f32 v71, v74, v75
	global_store_dwordx4 v[72:73], v[68:71], off sc1
	v_pk_mul_f32 v[74:75], v[54:55], v[66:67] op_sel_hi:[1,0]
	v_pk_mul_f32 v[76:77], v[52:53], v[66:67] op_sel_hi:[1,0]
	v_pk_mul_f32 v[70:71], v[62:63], v[66:67] op_sel_hi:[1,0]
	v_pk_mul_f32 v[68:69], v[60:61], v[66:67] op_sel_hi:[1,0]
	s_mov_b64 s[40:41], 0
	v_cvt_pk_bf16_f32 v68, v68, v69
	v_cvt_pk_bf16_f32 v69, v70, v71
	v_cvt_pk_bf16_f32 v70, v76, v77
	v_cvt_pk_bf16_f32 v71, v74, v75
	global_store_dwordx4 v[72:73], v[68:71], off offset:256 sc1

.LBB0_562:
	v_add_u32_e32 v52, 0x90, v130
	v_ashrrev_i32_e32 v53, 31, v52
	s_mov_b64 s[40:41], -1
	s_waitcnt vmcnt(7)
	v_add_f32_e32 v48, v166, v167
	v_add_f32_e32 v49, v168, v169
	v_add_f32_e32 v48, v48, v49
	v_mov_b32_e32 v49, v48
	s_nop 1
	v_permlane16_swap_b32_e32 v48, v49
	v_add_f32_e32 v48, v48, v49
	v_mov_b32_e32 v49, v48
	s_nop 1
	v_permlane32_swap_b32_e32 v48, v49
	v_add_f32_e32 v48, v48, v49
	v_fmamk_f32 v48, v48, 0x3a800000, v225
	v_rsq_f32_e32 v50, v48
	s_nop 0
	s_and_b64 vcc, exec, s[38:39]
	v_lshlrev_b64 v[48:49], 11, v[52:53]
	s_cbranch_vccnz .LBB0_564
	v_lshl_add_u64 v[52:53], s[26:27], 0, v[48:49]
	v_lshl_add_u64 v[52:53], s[68:69], 1, v[52:53]
	s_lshl_b32 s40, s62, 1
	s_mov_b32 s41, s69
	v_lshl_add_u64 v[52:53], v[52:53], 0, s[40:41]
	v_lshl_add_u64 v[56:57], v[52:53], 0, v[96:97]
	v_pk_mul_f32 v[54:55], v[46:47], v[50:51] op_sel_hi:[1,0]
	v_pk_mul_f32 v[52:53], v[44:45], v[50:51] op_sel_hi:[1,0]
	v_pk_mul_f32 v[58:59], v[38:39], v[50:51] op_sel_hi:[1,0]
	v_pk_mul_f32 v[60:61], v[36:37], v[50:51] op_sel_hi:[1,0]
	v_cvt_pk_bf16_f32 v52, v52, v53
	v_cvt_pk_bf16_f32 v53, v54, v55
	v_cvt_pk_bf16_f32 v54, v60, v61
	v_cvt_pk_bf16_f32 v55, v58, v59
	global_store_dwordx4 v[56:57], v[52:55], off sc1
	v_pk_mul_f32 v[58:59], v[34:35], v[50:51] op_sel_hi:[1,0]
	v_pk_mul_f32 v[60:61], v[32:33], v[50:51] op_sel_hi:[1,0]
	v_pk_mul_f32 v[54:55], v[42:43], v[50:51] op_sel_hi:[1,0]
	v_pk_mul_f32 v[52:53], v[40:41], v[50:51] op_sel_hi:[1,0]
	s_mov_b64 s[40:41], 0
	v_cvt_pk_bf16_f32 v52, v52, v53
	v_cvt_pk_bf16_f32 v53, v54, v55
	v_cvt_pk_bf16_f32 v54, v60, v61
	v_cvt_pk_bf16_f32 v55, v58, v59
	global_store_dwordx4 v[56:57], v[52:55], off offset:256 sc1

.LBB0_566:
	v_add_u32_e32 v36, 0xa0, v130
	v_ashrrev_i32_e32 v37, 31, v36
	s_mov_b64 s[40:41], -1
	s_waitcnt vmcnt(7)
	v_add_f32_e32 v32, v170, v171
	v_add_f32_e32 v33, v172, v173
	v_add_f32_e32 v32, v32, v33
	v_mov_b32_e32 v33, v32
	s_nop 1
	v_permlane16_swap_b32_e32 v32, v33
	v_add_f32_e32 v32, v32, v33
	v_mov_b32_e32 v33, v32
	s_nop 1
	v_permlane32_swap_b32_e32 v32, v33
	v_add_f32_e32 v32, v32, v33
	v_fmamk_f32 v32, v32, 0x3a800000, v225
	v_rsq_f32_e32 v34, v32
	s_nop 0
	s_and_b64 vcc, exec, s[38:39]
	v_lshlrev_b64 v[32:33], 11, v[36:37]
	s_cbranch_vccnz .LBB0_568
	v_lshl_add_u64 v[36:37], s[26:27], 0, v[32:33]
	v_lshl_add_u64 v[36:37], s[68:69], 1, v[36:37]
	s_lshl_b32 s40, s62, 1
	s_mov_b32 s41, s69
	v_lshl_add_u64 v[36:37], v[36:37], 0, s[40:41]
	v_lshl_add_u64 v[40:41], v[36:37], 0, v[96:97]
	v_pk_mul_f32 v[38:39], v[30:31], v[34:35] op_sel_hi:[1,0]
	v_pk_mul_f32 v[36:37], v[28:29], v[34:35] op_sel_hi:[1,0]
	v_pk_mul_f32 v[42:43], v[22:23], v[34:35] op_sel_hi:[1,0]
	v_pk_mul_f32 v[44:45], v[20:21], v[34:35] op_sel_hi:[1,0]
	v_cvt_pk_bf16_f32 v36, v36, v37
	v_cvt_pk_bf16_f32 v37, v38, v39
	v_cvt_pk_bf16_f32 v38, v44, v45
	v_cvt_pk_bf16_f32 v39, v42, v43
	global_store_dwordx4 v[40:41], v[36:39], off sc1
	v_pk_mul_f32 v[42:43], v[18:19], v[34:35] op_sel_hi:[1,0]
	v_pk_mul_f32 v[44:45], v[16:17], v[34:35] op_sel_hi:[1,0]
	v_pk_mul_f32 v[38:39], v[26:27], v[34:35] op_sel_hi:[1,0]
	v_pk_mul_f32 v[36:37], v[24:25], v[34:35] op_sel_hi:[1,0]
	s_mov_b64 s[40:41], 0
	v_cvt_pk_bf16_f32 v36, v36, v37
	v_cvt_pk_bf16_f32 v37, v38, v39
	v_cvt_pk_bf16_f32 v38, v44, v45
	v_cvt_pk_bf16_f32 v39, v42, v43
	global_store_dwordx4 v[40:41], v[36:39], off offset:256 sc1

.LBB0_570:
	v_add_u32_e32 v20, 0xb0, v130
	v_ashrrev_i32_e32 v21, 31, v20
	s_mov_b64 s[40:41], -1
	s_waitcnt vmcnt(7)
	v_add_f32_e32 v16, v174, v175
	v_add_f32_e32 v17, v176, v177
	v_add_f32_e32 v16, v16, v17
	v_mov_b32_e32 v17, v16
	s_nop 1
	v_permlane16_swap_b32_e32 v16, v17
	v_add_f32_e32 v16, v16, v17
	v_mov_b32_e32 v17, v16
	s_nop 1
	v_permlane32_swap_b32_e32 v16, v17
	v_add_f32_e32 v16, v16, v17
	v_fmamk_f32 v16, v16, 0x3a800000, v225
	v_rsq_f32_e32 v18, v16
	s_nop 0
	s_and_b64 vcc, exec, s[38:39]
	v_lshlrev_b64 v[16:17], 11, v[20:21]
	s_cbranch_vccz .LBB0_573
	s_andn2_b64 vcc, exec, s[40:41]
	s_cbranch_vccz .LBB0_574
